# hyena: batched z0 conv loads; gating rows staged through LDS with coalesced 16B loads instead of serialized scattered 2B loads
# speedup vs baseline: 1.1402x; 1.1402x over previous
.LBB0_1039:
	s_add_i32 s2, s56, 0xfffffc00
	s_cmpk_gt_i32 s56, 0x3ff
	s_cselect_b32 s2, s2, s56
	s_ashr_i32 s16, s2, 1
	s_and_b32 s30, s2, 1
	s_cmpk_lt_i32 s56, 0x400
	s_mov_b64 s[2:3], -1
	s_cbranch_scc0 .LBB0_1048
	s_mov_b64 s[2:3], s[0:1]
	s_load_dwordx2 s[6:7], s[2:3], 0x128
	s_mov_b64 s[2:3], s[0:1]
	s_load_dwordx2 s[8:9], s[2:3], 0x128
	s_mov_b64 s[2:3], s[0:1]
	s_load_dwordx2 s[2:3], s[2:3], 0x128
	v_mbcnt_lo_u32_b32 v0, -1, 0
	v_mbcnt_hi_u32_b32 v0, -1, v0
	s_mov_b64 s[10:11], s[0:1]
	v_add_u32_e32 v0, s33, v0
	s_load_dwordx2 s[10:11], s[10:11], 0x68
	s_mov_b64 s[12:13], s[0:1]
	s_load_dwordx2 s[12:13], s[12:13], 0x70
	s_waitcnt lgkmcnt(0)
	s_add_u32 s18, s8, 0x10f90100
	s_addc_u32 s19, s9, 0
	s_lshl_b32 s31, s30, 1
	s_add_u32 s46, s10, s22
	s_addc_u32 s47, s11, 0
	s_add_u32 s8, s12, s23
	s_addc_u32 s9, s13, 0
	s_ashr_i32 s17, s16, 31
	s_lshl_b64 s[26:27], s[16:17], 2
	s_add_u32 s36, s46, s26
	s_addc_u32 s37, s47, s27
	s_add_u32 s38, s36, 0x3000
	s_addc_u32 s39, s37, 0
	s_add_u32 s40, s8, s26
	s_movk_i32 s8, 0x2000
	s_addc_u32 s41, s9, s27
	v_cmp_gt_i32_e32 vcc, s8, v0
	s_and_saveexec_b64 s[8:9], vcc
	s_cbranch_execz .LBB0_1069
	global_load_dword v8, v1, s[36:37]
	global_load_dword v9, v1, s[38:39]
	global_load_dword v10, v1, s[40:41]
	v_mov_b32_e32 v2, 0x1000
	global_load_dword v11, v2, s[36:37] offset:2048
	s_mul_i32 s10, s31, s87
	s_add_i32 s10, s10, s16
	s_ashr_i32 s11, s10, 31
	s_lshl_b64 s[10:11], s[10:11], 13
	s_add_u32 s10, s10, s18
	s_addc_u32 s11, s11, s19
	s_add_u32 s12, s10, 0xc00000
	s_addc_u32 s13, s11, 0
	v_lshlrev_b32_e32 v12, 1, v0
	v_add_u32_e32 v13, 0x1000, v12
	v_lshrrev_b32_e32 v14, 8, v0
	v_and_b32_e32 v15, 0xff, v0
	v_mov_b32_e32 v2, s52
	v_mad_i32_i24 v14, v14, s53, v2
	v_lshl_add_u32 v14, v15, 1, v14
	global_load_ushort v32, v12, s[10:11]
	global_load_ushort v48, v12, s[10:11] offset:-2
	global_load_ushort v64, v12, s[10:11] offset:2
	global_load_ushort v33, v12, s[10:11] offset:1024
	global_load_ushort v49, v12, s[10:11] offset:1022
	global_load_ushort v65, v12, s[10:11] offset:1026
	global_load_ushort v34, v12, s[10:11] offset:2048
	global_load_ushort v50, v12, s[10:11] offset:2046
	global_load_ushort v66, v12, s[10:11] offset:2050
	global_load_ushort v35, v12, s[10:11] offset:3072
	global_load_ushort v51, v12, s[10:11] offset:3070
	global_load_ushort v67, v12, s[10:11] offset:3074
	global_load_ushort v36, v13, s[10:11]
	global_load_ushort v52, v13, s[10:11] offset:-2
	global_load_ushort v68, v13, s[10:11] offset:2
	global_load_ushort v37, v13, s[10:11] offset:1024
	global_load_ushort v53, v13, s[10:11] offset:1022
	global_load_ushort v69, v13, s[10:11] offset:1026
	global_load_ushort v38, v13, s[10:11] offset:2048
	global_load_ushort v54, v13, s[10:11] offset:2046
	global_load_ushort v70, v13, s[10:11] offset:2050
	global_load_ushort v39, v13, s[10:11] offset:3072
	global_load_ushort v55, v13, s[10:11] offset:3070
	global_load_ushort v71, v13, s[10:11] offset:3074
	global_load_ushort v40, v12, s[12:13]
	global_load_ushort v56, v12, s[12:13] offset:-2
	global_load_ushort v72, v12, s[12:13] offset:2
	global_load_ushort v41, v12, s[12:13] offset:1024
	global_load_ushort v57, v12, s[12:13] offset:1022
	global_load_ushort v73, v12, s[12:13] offset:1026
	global_load_ushort v42, v12, s[12:13] offset:2048
	global_load_ushort v58, v12, s[12:13] offset:2046
	global_load_ushort v74, v12, s[12:13] offset:2050
	global_load_ushort v43, v12, s[12:13] offset:3072
	global_load_ushort v59, v12, s[12:13] offset:3070
	global_load_ushort v75, v12, s[12:13] offset:3074
	global_load_ushort v44, v13, s[12:13]
	global_load_ushort v60, v13, s[12:13] offset:-2
	global_load_ushort v76, v13, s[12:13] offset:2
	global_load_ushort v45, v13, s[12:13] offset:1024
	global_load_ushort v61, v13, s[12:13] offset:1022
	global_load_ushort v77, v13, s[12:13] offset:1026
	global_load_ushort v46, v13, s[12:13] offset:2048
	global_load_ushort v62, v13, s[12:13] offset:2046
	global_load_ushort v78, v13, s[12:13] offset:2050
	global_load_ushort v47, v13, s[12:13] offset:3072
	global_load_ushort v63, v13, s[12:13] offset:3070
	global_load_ushort v79, v13, s[12:13] offset:3074
	v_cmp_ne_u32_e32 vcc, 0, v0
	s_waitcnt vmcnt(0)
	s_nop 1
	v_cndmask_b32_e32 v48, 0, v48, vcc
	v_cndmask_b32_e32 v56, 0, v56, vcc
	s_movk_i32 s10, 0x1ff
	v_cmp_ne_u32_e32 vcc, s10, v0
	s_nop 1
	v_cndmask_b32_e32 v71, 0, v71, vcc
	v_cndmask_b32_e32 v79, 0, v79, vcc
	v_lshlrev_b32_e32 v32, 16, v32
	v_lshlrev_b32_e32 v48, 16, v48
	v_lshlrev_b32_e32 v64, 16, v64
	v_fma_f32 v32, v11, v32, v10
	v_fmac_f32_e32 v32, v8, v48
	v_fmac_f32_e32 v32, v9, v64
	v_cvt_pk_bf16_f32 v32, v32, v32
	ds_write_b16 v14, v32
	v_lshlrev_b32_e32 v33, 16, v33
	v_lshlrev_b32_e32 v49, 16, v49
	v_lshlrev_b32_e32 v65, 16, v65
	v_fma_f32 v33, v11, v33, v10
	v_fmac_f32_e32 v33, v8, v49
	v_fmac_f32_e32 v33, v9, v65
	v_cvt_pk_bf16_f32 v33, v33, v33
	ds_write_b16 v14, v33 offset:1056
	v_lshlrev_b32_e32 v34, 16, v34
	v_lshlrev_b32_e32 v50, 16, v50
	v_lshlrev_b32_e32 v66, 16, v66
	v_fma_f32 v34, v11, v34, v10
	v_fmac_f32_e32 v34, v8, v50
	v_fmac_f32_e32 v34, v9, v66
	v_cvt_pk_bf16_f32 v34, v34, v34
	ds_write_b16 v14, v34 offset:2112
	v_lshlrev_b32_e32 v35, 16, v35
	v_lshlrev_b32_e32 v51, 16, v51
	v_lshlrev_b32_e32 v67, 16, v67
	v_fma_f32 v35, v11, v35, v10
	v_fmac_f32_e32 v35, v8, v51
	v_fmac_f32_e32 v35, v9, v67
	v_cvt_pk_bf16_f32 v35, v35, v35
	ds_write_b16 v14, v35 offset:3168
	v_lshlrev_b32_e32 v36, 16, v36
	v_lshlrev_b32_e32 v52, 16, v52
	v_lshlrev_b32_e32 v68, 16, v68
	v_fma_f32 v36, v11, v36, v10
	v_fmac_f32_e32 v36, v8, v52
	v_fmac_f32_e32 v36, v9, v68
	v_cvt_pk_bf16_f32 v36, v36, v36
	ds_write_b16 v14, v36 offset:4224
	v_lshlrev_b32_e32 v37, 16, v37
	v_lshlrev_b32_e32 v53, 16, v53
	v_lshlrev_b32_e32 v69, 16, v69
	v_fma_f32 v37, v11, v37, v10
	v_fmac_f32_e32 v37, v8, v53
	v_fmac_f32_e32 v37, v9, v69
	v_cvt_pk_bf16_f32 v37, v37, v37
	ds_write_b16 v14, v37 offset:5280
	v_lshlrev_b32_e32 v38, 16, v38
	v_lshlrev_b32_e32 v54, 16, v54
	v_lshlrev_b32_e32 v70, 16, v70
	v_fma_f32 v38, v11, v38, v10
	v_fmac_f32_e32 v38, v8, v54
	v_fmac_f32_e32 v38, v9, v70
	v_cvt_pk_bf16_f32 v38, v38, v38
	ds_write_b16 v14, v38 offset:6336
	v_lshlrev_b32_e32 v39, 16, v39
	v_lshlrev_b32_e32 v55, 16, v55
	v_lshlrev_b32_e32 v71, 16, v71
	v_fma_f32 v39, v11, v39, v10
	v_fmac_f32_e32 v39, v8, v55
	v_fmac_f32_e32 v39, v9, v71
	v_cvt_pk_bf16_f32 v39, v39, v39
	ds_write_b16 v14, v39 offset:7392
	v_lshlrev_b32_e32 v40, 16, v40
	v_lshlrev_b32_e32 v56, 16, v56
	v_lshlrev_b32_e32 v72, 16, v72
	v_fma_f32 v40, v11, v40, v10
	v_fmac_f32_e32 v40, v8, v56
	v_fmac_f32_e32 v40, v9, v72
	v_cvt_pk_bf16_f32 v40, v40, v40
	ds_write_b16 v14, v40 offset:8576
	v_lshlrev_b32_e32 v41, 16, v41
	v_lshlrev_b32_e32 v57, 16, v57
	v_lshlrev_b32_e32 v73, 16, v73
	v_fma_f32 v41, v11, v41, v10
	v_fmac_f32_e32 v41, v8, v57
	v_fmac_f32_e32 v41, v9, v73
	v_cvt_pk_bf16_f32 v41, v41, v41
	ds_write_b16 v14, v41 offset:9632
	v_lshlrev_b32_e32 v42, 16, v42
	v_lshlrev_b32_e32 v58, 16, v58
	v_lshlrev_b32_e32 v74, 16, v74
	v_fma_f32 v42, v11, v42, v10
	v_fmac_f32_e32 v42, v8, v58
	v_fmac_f32_e32 v42, v9, v74
	v_cvt_pk_bf16_f32 v42, v42, v42
	ds_write_b16 v14, v42 offset:10688
	v_lshlrev_b32_e32 v43, 16, v43
	v_lshlrev_b32_e32 v59, 16, v59
	v_lshlrev_b32_e32 v75, 16, v75
	v_fma_f32 v43, v11, v43, v10
	v_fmac_f32_e32 v43, v8, v59
	v_fmac_f32_e32 v43, v9, v75
	v_cvt_pk_bf16_f32 v43, v43, v43
	ds_write_b16 v14, v43 offset:11744
	v_lshlrev_b32_e32 v44, 16, v44
	v_lshlrev_b32_e32 v60, 16, v60
	v_lshlrev_b32_e32 v76, 16, v76
	v_fma_f32 v44, v11, v44, v10
	v_fmac_f32_e32 v44, v8, v60
	v_fmac_f32_e32 v44, v9, v76
	v_cvt_pk_bf16_f32 v44, v44, v44
	ds_write_b16 v14, v44 offset:12800
	v_lshlrev_b32_e32 v45, 16, v45
	v_lshlrev_b32_e32 v61, 16, v61
	v_lshlrev_b32_e32 v77, 16, v77
	v_fma_f32 v45, v11, v45, v10
	v_fmac_f32_e32 v45, v8, v61
	v_fmac_f32_e32 v45, v9, v77
	v_cvt_pk_bf16_f32 v45, v45, v45
	ds_write_b16 v14, v45 offset:13856
	v_lshlrev_b32_e32 v46, 16, v46
	v_lshlrev_b32_e32 v62, 16, v62
	v_lshlrev_b32_e32 v78, 16, v78
	v_fma_f32 v46, v11, v46, v10
	v_fmac_f32_e32 v46, v8, v62
	v_fmac_f32_e32 v46, v9, v78
	v_cvt_pk_bf16_f32 v46, v46, v46
	ds_write_b16 v14, v46 offset:14912
	v_lshlrev_b32_e32 v47, 16, v47
	v_lshlrev_b32_e32 v63, 16, v63
	v_lshlrev_b32_e32 v79, 16, v79
	v_fma_f32 v47, v11, v47, v10
	v_fmac_f32_e32 v47, v8, v63
	v_fmac_f32_e32 v47, v9, v79
	v_cvt_pk_bf16_f32 v47, v47, v47
	ds_write_b16 v14, v47 offset:15968
	s_branch .LBB0_1069
.LBB0_1048:
	s_and_b64 vcc, exec, s[2:3]
	s_cbranch_vccz .LBB0_1038
	s_branch .LBB0_1217
.LBB0_1069:
	s_or_b64 exec, exec, s[8:9]
	v_ashrrev_i32_e32 v3, 6, v0
	v_lshlrev_b32_e32 v5, 2, v3
	v_add_u32_e32 v169, -15, v5
	v_add_u32_e32 v5, -11, v5
	v_cmp_ne_u32_e32 vcc, 7, v3
	s_add_u32 s48, s6, s5
	s_addc_u32 s49, s7, 0
	v_cndmask_b32_e32 v170, 16, v5, vcc
	v_lshrrev_b32_e32 v5, 1, v0
	v_and_b32_e32 v171, 16, v5
	v_and_b32_e32 v5, 1, v0
	s_lshl_b64 s[8:9], s[16:17], 1
	v_cmp_eq_u32_e32 vcc, 1, v5
	v_mov_b32_e32 v5, 0x2180
	s_add_u32 s2, s2, s8
	v_cndmask_b32_e32 v5, 0, v5, vcc
	s_addc_u32 s3, s3, s9
	v_and_b32_e32 v2, 63, v0
	v_and_b32_e32 v4, 31, v0
	v_add3_u32 v172, s52, v5, v171
	v_lshlrev_b32_e32 v5, 15, v3
	s_add_u32 s20, s2, 0x2adf0d00
	s_movk_i32 s2, 0x100
	v_bfe_u32 v168, v0, 1, 4
	v_lshl_add_u32 v2, v2, 2, 0
	v_and_b32_e32 v6, 0x18000, v5
	v_cmp_gt_u32_e64 s[8:9], s2, v0
	v_and_b32_e32 v0, 0xffffff00, v0
	v_lshlrev_b32_e32 v223, 4, v4
	v_lshl_add_u32 v173, v3, 12, v2
	v_add_u32_e32 v221, v2, v5
	v_cmp_eq_u32_e64 s[10:11], s2, v0
	v_add_u32_e32 v222, v2, v6
	v_sub_u32_e32 v0, v171, v223
	v_lshlrev_b32_e32 v2, 11, v3
	v_sub_u32_e32 v0, v0, v2
	v_cmp_lt_i32_e64 s[6:7], v169, v170
	s_mov_b32 s66, 0
	s_addc_u32 s21, s3, 0
	v_add_u32_e32 v174, 0x10000, v173
	v_add_u32_e32 v175, 0x10100, v173
	v_add_u32_e32 v176, 0x10200, v173
	v_add_u32_e32 v177, 0x10300, v173
	v_add_u32_e32 v178, 0x10400, v173
	v_add_u32_e32 v179, 0x10500, v173
	v_add_u32_e32 v180, 0x10600, v173
	v_add_u32_e32 v181, 0x10700, v173
	v_add_u32_e32 v182, 0x10800, v173
	v_add_u32_e32 v183, 0x10900, v173
	v_add_u32_e32 v184, 0x10a00, v173
	v_add_u32_e32 v185, 0x10b00, v173
	v_add_u32_e32 v186, 0x10c00, v173
	v_add_u32_e32 v187, 0x10d00, v173
	v_add_u32_e32 v188, 0x10e00, v173
	v_add_u32_e32 v189, 0x10f00, v173
	v_add_u32_e32 v190, 0x18000, v173
	v_add_u32_e32 v191, 0x18100, v173
	v_add_u32_e32 v192, 0x18200, v173
	v_add_u32_e32 v193, 0x18300, v173
	v_add_u32_e32 v202, 0x18400, v173
	v_add_u32_e32 v203, 0x18500, v173
	v_add_u32_e32 v204, 0x18600, v173
	v_add_u32_e32 v205, 0x18700, v173
	v_add_u32_e32 v213, 0x18800, v173
	v_add_u32_e32 v214, 0x18900, v173
	v_add_u32_e32 v215, 0x18a00, v173
	v_add_u32_e32 v216, 0x18b00, v173
	v_add_u32_e32 v217, 0x18c00, v173
	v_add_u32_e32 v218, 0x18d00, v173
	v_add_u32_e32 v219, 0x18e00, v173
	v_add_u32_e32 v220, 0x18f00, v173
	v_add_u32_e32 v224, 0, v0
	s_mov_b64 s[2:3], -1
	s_branch .LBB0_1071

.LBB0_1088:
	s_or_b64 exec, exec, s[12:13]
	s_and_b64 s[2:3], s[2:3], exec
	s_cselect_b32 s2, s54, 0x400
	s_barrier
	s_barrier
	v_mbcnt_lo_u32_b32 v0, -1, 0
	v_mbcnt_hi_u32_b32 v0, -1, v0
	s_add_i32 s12, s2, s16
	s_lshl_b32 s2, s2, 2
	v_add_u32_e32 v4, s33, v0
	v_mov_b32_e32 v0, s2
	s_add_i32 s2, s12, 0x600
	s_ashr_i32 s3, s2, 31
	s_lshl_b64 s[2:3], s[2:3], 2
	s_add_u32 s2, s46, s2
	s_addc_u32 s3, s47, s3
	global_load_dword v10, v0, s[36:37]
	global_load_dword v9, v0, s[38:39]
	global_load_dword v8, v0, s[40:41]
	global_load_dword v12, v1, s[2:3]
	s_mov_b64 s[2:3], s[0:1]
	s_load_dwordx2 s[2:3], s[2:3], 0xb8
	v_and_b32_e32 v13, 1, v4
	v_or_b32_e32 v0, s31, v13
	v_ashrrev_i32_e32 v5, 6, v4
	s_waitcnt lgkmcnt(0)
	s_add_u32 s13, s2, s14
	s_addc_u32 s17, s3, s15
	s_lshl_b64 s[2:3], s[66:67], 2
	s_add_u32 s2, s13, s2
	s_addc_u32 s3, s17, s3
	s_add_u32 s2, s2, s26
	s_addc_u32 s3, s3, s27
	global_load_dword v11, v1, s[2:3]
	s_mul_i32 s2, s31, s87
	s_add_i32 s2, s2, s12
	s_ashr_i32 s3, s2, 31
	s_lshl_b64 s[2:3], s[2:3], 13
	s_add_u32 s2, s2, s18
	s_addc_u32 s3, s3, s19
	s_add_u32 s12, s2, 0xc00000
	s_addc_u32 s13, s3, 0
	v_lshlrev_b32_e32 v2, 4, v4
	global_load_dwordx4 v[32:35], v2, s[2:3]
	global_load_dwordx4 v[36:39], v2, s[12:13]
	v_lshrrev_b32_e32 v2, 5, v4
	v_and_b32_e32 v3, 31, v4
	v_mul_u32_u24_e32 v2, 0x210, v2
	v_lshl_add_u32 v2, v3, 4, v2
	v_lshlrev_b32_e32 v6, 7, v4
	v_and_b32_e32 v4, 32, v4
	s_movk_i32 s2, 0xf00
	v_and_or_b32 v4, v6, s2, v4
	v_add_u32_e32 v6, v5, v4
	v_mov_b32_e32 v14, s52
	s_movk_i32 s2, 0x2180
	v_mad_u32_u24 v13, v13, s2, v14
	v_lshrrev_b32_e32 v14, 8, v6
	v_lshlrev_b32_e32 v15, 1, v6
	v_and_b32_e32 v15, 0x1fe, v15
	v_mad_i32_i24 v14, v14, s53, v13
	v_add_u32_e32 v14, v14, v15
	v_lshlrev_b32_e32 v7, 12, v0
	v_subrev_u32_e32 v3, s52, v14
	v_mov_b32_e32 v5, 18
	v_and_b32_e32 v4, 0xff, v6
	v_cmp_eq_u32_e32 vcc, 0, v4
	v_add_u32_e32 v13, 0xd8, v6
	s_nop 0
	v_cndmask_b32_e32 v4, 2, v5, vcc
	v_cmp_eq_u32_e32 vcc, 0, v6
	v_and_b32_e32 v0, 0xff, v13
	s_nop 0
	v_cndmask_b32_e32 v4, v4, v1, vcc
	s_movk_i32 s2, 0xff
	v_cmp_eq_u32_e32 vcc, s2, v0
	v_sub_u32_e32 v4, v3, v4
	s_nop 0
	v_cndmask_b32_e32 v0, 2, v5, vcc
	v_cmp_eq_u32_e32 vcc, s85, v13
	s_nop 1
	v_cndmask_b32_e32 v0, v0, v1, vcc
	v_add_u32_e32 v5, v3, v0
	s_waitcnt vmcnt(0)
	ds_write_b128 v2, v[32:35]
	ds_write_b128 v2, v[36:39] offset:8576
	s_waitcnt lgkmcnt(0)
	s_barrier
	ds_read_u16 v32, v3
	ds_read_u16 v48, v4
	ds_read_u16 v64, v3 offset:2
	ds_read_u16 v33, v3 offset:16
	ds_read_u16 v49, v3 offset:14
	ds_read_u16 v65, v3 offset:18
	ds_read_u16 v34, v3 offset:32
	ds_read_u16 v50, v3 offset:30
	ds_read_u16 v66, v3 offset:34
	ds_read_u16 v35, v3 offset:48
	ds_read_u16 v51, v3 offset:46
	ds_read_u16 v67, v3 offset:50
	ds_read_u16 v36, v3 offset:128
	ds_read_u16 v52, v3 offset:126
	ds_read_u16 v68, v3 offset:130
	ds_read_u16 v37, v3 offset:144
	ds_read_u16 v53, v3 offset:142
	ds_read_u16 v69, v3 offset:146
	ds_read_u16 v38, v3 offset:160
	ds_read_u16 v54, v3 offset:158
	ds_read_u16 v70, v3 offset:162
	ds_read_u16 v39, v3 offset:176
	ds_read_u16 v55, v3 offset:174
	ds_read_u16 v71, v3 offset:178
	ds_read_u16 v40, v3 offset:256
	ds_read_u16 v56, v3 offset:254
	ds_read_u16 v72, v3 offset:258
	ds_read_u16 v41, v3 offset:272
	ds_read_u16 v57, v3 offset:270
	ds_read_u16 v73, v3 offset:274
	ds_read_u16 v42, v3 offset:288
	ds_read_u16 v58, v3 offset:286
	ds_read_u16 v74, v3 offset:290
	ds_read_u16 v43, v3 offset:304
	ds_read_u16 v59, v3 offset:302
	ds_read_u16 v75, v3 offset:306
	ds_read_u16 v44, v3 offset:384
	ds_read_u16 v60, v3 offset:382
	ds_read_u16 v76, v3 offset:386
	ds_read_u16 v45, v3 offset:400
	ds_read_u16 v61, v3 offset:398
	ds_read_u16 v77, v3 offset:402
	ds_read_u16 v46, v3 offset:416
	ds_read_u16 v62, v3 offset:414
	ds_read_u16 v78, v3 offset:418
	ds_read_u16 v47, v3 offset:432
	ds_read_u16 v63, v3 offset:430
	ds_read_u16 v79, v5 offset:432
	ds_read_u16 v80, v14
	ds_read_u16 v81, v14 offset:16
	ds_read_u16 v82, v14 offset:32
	ds_read_u16 v83, v14 offset:48
	ds_read_u16 v84, v14 offset:128
	ds_read_u16 v85, v14 offset:144
	ds_read_u16 v86, v14 offset:160
	ds_read_u16 v87, v14 offset:176
	ds_read_u16 v88, v14 offset:256
	ds_read_u16 v89, v14 offset:272
	ds_read_u16 v90, v14 offset:288
	ds_read_u16 v91, v14 offset:304
	ds_read_u16 v92, v14 offset:384
	ds_read_u16 v93, v14 offset:400
	ds_read_u16 v94, v14 offset:416
	ds_read_u16 v95, v14 offset:432
	v_add_u32_e32 v15, v6, v7
	v_lshlrev_b32_e32 v15, 12, v15
	v_cmp_lt_i32_e32 vcc, 0, v6
	s_waitcnt lgkmcnt(0)
	s_nop 1
	v_cndmask_b32_e32 v48, 0, v48, vcc
	v_cmp_gt_i32_e32 vcc, s85, v13
	s_nop 1
	v_cndmask_b32_e32 v79, 0, v79, vcc
	v_lshlrev_b32_e32 v32, 16, v32
	v_lshlrev_b32_e32 v48, 16, v48
	v_lshlrev_b32_e32 v64, 16, v64
	v_fma_f32 v32, v12, v32, v8
	v_fmac_f32_e32 v32, v10, v48
	v_fmac_f32_e32 v32, v9, v64
	v_lshlrev_b32_e32 v80, 16, v80
	v_fma_f32 v80, v11, v80, v16
	v_mul_f32_e32 v80, v80, v32
	v_cvt_pk_bf16_f32 v80, v80, v80
	v_lshlrev_b32_e32 v33, 16, v33
	v_lshlrev_b32_e32 v49, 16, v49
	v_lshlrev_b32_e32 v65, 16, v65
	v_fma_f32 v33, v12, v33, v8
	v_fmac_f32_e32 v33, v10, v49
	v_fmac_f32_e32 v33, v9, v65
	v_lshlrev_b32_e32 v81, 16, v81
	v_fma_f32 v81, v11, v81, v17
	v_mul_f32_e32 v81, v81, v33
	v_cvt_pk_bf16_f32 v81, v81, v81
	v_lshlrev_b32_e32 v34, 16, v34
	v_lshlrev_b32_e32 v50, 16, v50
	v_lshlrev_b32_e32 v66, 16, v66
	v_fma_f32 v34, v12, v34, v8
	v_fmac_f32_e32 v34, v10, v50
	v_fmac_f32_e32 v34, v9, v66
	v_lshlrev_b32_e32 v82, 16, v82
	v_fma_f32 v82, v11, v82, v18
	v_mul_f32_e32 v82, v82, v34
	v_cvt_pk_bf16_f32 v82, v82, v82
	v_lshlrev_b32_e32 v35, 16, v35
	v_lshlrev_b32_e32 v51, 16, v51
	v_lshlrev_b32_e32 v67, 16, v67
	v_fma_f32 v35, v12, v35, v8
	v_fmac_f32_e32 v35, v10, v51
	v_fmac_f32_e32 v35, v9, v67
	v_lshlrev_b32_e32 v83, 16, v83
	v_fma_f32 v83, v11, v83, v19
	v_mul_f32_e32 v83, v83, v35
	v_cvt_pk_bf16_f32 v83, v83, v83
	v_lshlrev_b32_e32 v36, 16, v36
	v_lshlrev_b32_e32 v52, 16, v52
	v_lshlrev_b32_e32 v68, 16, v68
	v_fma_f32 v36, v12, v36, v8
	v_fmac_f32_e32 v36, v10, v52
	v_fmac_f32_e32 v36, v9, v68
	v_lshlrev_b32_e32 v84, 16, v84
	v_fma_f32 v84, v11, v84, v20
	v_mul_f32_e32 v84, v84, v36
	v_cvt_pk_bf16_f32 v84, v84, v84
	v_lshlrev_b32_e32 v37, 16, v37
	v_lshlrev_b32_e32 v53, 16, v53
	v_lshlrev_b32_e32 v69, 16, v69
	v_fma_f32 v37, v12, v37, v8
	v_fmac_f32_e32 v37, v10, v53
	v_fmac_f32_e32 v37, v9, v69
	v_lshlrev_b32_e32 v85, 16, v85
	v_fma_f32 v85, v11, v85, v21
	v_mul_f32_e32 v85, v85, v37
	v_cvt_pk_bf16_f32 v85, v85, v85
	v_lshlrev_b32_e32 v38, 16, v38
	v_lshlrev_b32_e32 v54, 16, v54
	v_lshlrev_b32_e32 v70, 16, v70
	v_fma_f32 v38, v12, v38, v8
	v_fmac_f32_e32 v38, v10, v54
	v_fmac_f32_e32 v38, v9, v70
	v_lshlrev_b32_e32 v86, 16, v86
	v_fma_f32 v86, v11, v86, v22
	v_mul_f32_e32 v86, v86, v38
	v_cvt_pk_bf16_f32 v86, v86, v86
	v_lshlrev_b32_e32 v39, 16, v39
	v_lshlrev_b32_e32 v55, 16, v55
	v_lshlrev_b32_e32 v71, 16, v71
	v_fma_f32 v39, v12, v39, v8
	v_fmac_f32_e32 v39, v10, v55
	v_fmac_f32_e32 v39, v9, v71
	v_lshlrev_b32_e32 v87, 16, v87
	v_fma_f32 v87, v11, v87, v23
	v_mul_f32_e32 v87, v87, v39
	v_cvt_pk_bf16_f32 v87, v87, v87
	v_lshlrev_b32_e32 v40, 16, v40
	v_lshlrev_b32_e32 v56, 16, v56
	v_lshlrev_b32_e32 v72, 16, v72
	v_fma_f32 v40, v12, v40, v8
	v_fmac_f32_e32 v40, v10, v56
	v_fmac_f32_e32 v40, v9, v72
	v_lshlrev_b32_e32 v88, 16, v88
	v_fma_f32 v88, v11, v88, v24
	v_mul_f32_e32 v88, v88, v40
	v_cvt_pk_bf16_f32 v88, v88, v88
	v_lshlrev_b32_e32 v41, 16, v41
	v_lshlrev_b32_e32 v57, 16, v57
	v_lshlrev_b32_e32 v73, 16, v73
	v_fma_f32 v41, v12, v41, v8
	v_fmac_f32_e32 v41, v10, v57
	v_fmac_f32_e32 v41, v9, v73
	v_lshlrev_b32_e32 v89, 16, v89
	v_fma_f32 v89, v11, v89, v25
	v_mul_f32_e32 v89, v89, v41
	v_cvt_pk_bf16_f32 v89, v89, v89
	v_lshlrev_b32_e32 v42, 16, v42
	v_lshlrev_b32_e32 v58, 16, v58
	v_lshlrev_b32_e32 v74, 16, v74
	v_fma_f32 v42, v12, v42, v8
	v_fmac_f32_e32 v42, v10, v58
	v_fmac_f32_e32 v42, v9, v74
	v_lshlrev_b32_e32 v90, 16, v90
	v_fma_f32 v90, v11, v90, v26
	v_mul_f32_e32 v90, v90, v42
	v_cvt_pk_bf16_f32 v90, v90, v90
	v_lshlrev_b32_e32 v43, 16, v43
	v_lshlrev_b32_e32 v59, 16, v59
	v_lshlrev_b32_e32 v75, 16, v75
	v_fma_f32 v43, v12, v43, v8
	v_fmac_f32_e32 v43, v10, v59
	v_fmac_f32_e32 v43, v9, v75
	v_lshlrev_b32_e32 v91, 16, v91
	v_fma_f32 v91, v11, v91, v27
	v_mul_f32_e32 v91, v91, v43
	v_cvt_pk_bf16_f32 v91, v91, v91
	v_lshlrev_b32_e32 v44, 16, v44
	v_lshlrev_b32_e32 v60, 16, v60
	v_lshlrev_b32_e32 v76, 16, v76
	v_fma_f32 v44, v12, v44, v8
	v_fmac_f32_e32 v44, v10, v60
	v_fmac_f32_e32 v44, v9, v76
	v_lshlrev_b32_e32 v92, 16, v92
	v_fma_f32 v92, v11, v92, v28
	v_mul_f32_e32 v92, v92, v44
	v_cvt_pk_bf16_f32 v92, v92, v92
	v_lshlrev_b32_e32 v45, 16, v45
	v_lshlrev_b32_e32 v61, 16, v61
	v_lshlrev_b32_e32 v77, 16, v77
	v_fma_f32 v45, v12, v45, v8
	v_fmac_f32_e32 v45, v10, v61
	v_fmac_f32_e32 v45, v9, v77
	v_lshlrev_b32_e32 v93, 16, v93
	v_fma_f32 v93, v11, v93, v29
	v_mul_f32_e32 v93, v93, v45
	v_cvt_pk_bf16_f32 v93, v93, v93
	v_lshlrev_b32_e32 v46, 16, v46
	v_lshlrev_b32_e32 v62, 16, v62
	v_lshlrev_b32_e32 v78, 16, v78
	v_fma_f32 v46, v12, v46, v8
	v_fmac_f32_e32 v46, v10, v62
	v_fmac_f32_e32 v46, v9, v78
	v_lshlrev_b32_e32 v94, 16, v94
	v_fma_f32 v94, v11, v94, v30
	v_mul_f32_e32 v94, v94, v46
	v_cvt_pk_bf16_f32 v94, v94, v94
	v_lshlrev_b32_e32 v47, 16, v47
	v_lshlrev_b32_e32 v63, 16, v63
	v_lshlrev_b32_e32 v79, 16, v79
	v_fma_f32 v47, v12, v47, v8
	v_fmac_f32_e32 v47, v10, v63
	v_fmac_f32_e32 v47, v9, v79
	v_lshlrev_b32_e32 v95, 16, v95
	v_fma_f32 v95, v11, v95, v31
	v_mul_f32_e32 v95, v95, v47
	v_cvt_pk_bf16_f32 v95, v95, v95
	s_andn2_b64 s[12:13], exec, s[24:25]
	s_and_b64 vcc, exec, s[24:25]
	s_cbranch_vccnz .Lhy_gate_store
	ds_write_b16 v14, v80
	ds_write_b16 v14, v81 offset:16
	ds_write_b16 v14, v82 offset:32
	ds_write_b16 v14, v83 offset:48
	ds_write_b16 v14, v84 offset:128
	ds_write_b16 v14, v85 offset:144
	ds_write_b16 v14, v86 offset:160
	ds_write_b16 v14, v87 offset:176
	ds_write_b16 v14, v88 offset:256
	ds_write_b16 v14, v89 offset:272
	ds_write_b16 v14, v90 offset:288
	ds_write_b16 v14, v91 offset:304
	ds_write_b16 v14, v92 offset:384
	ds_write_b16 v14, v93 offset:400
	ds_write_b16 v14, v94 offset:416
	ds_write_b16 v14, v95 offset:432
	s_branch .LBB0_1070
.Lhy_gate_store:
	global_store_short v15, v80, s[20:21]
	v_add_u32_e32 v33, 0x8000, v15
	global_store_short v33, v81, s[20:21]
	v_add_u32_e32 v34, 0x10000, v15
	global_store_short v34, v82, s[20:21]
	v_add_u32_e32 v35, 0x18000, v15
	global_store_short v35, v83, s[20:21]
	v_add_u32_e32 v36, 0x40000, v15
	global_store_short v36, v84, s[20:21]
	v_add_u32_e32 v37, 0x48000, v15
	global_store_short v37, v85, s[20:21]
	v_add_u32_e32 v38, 0x50000, v15
	global_store_short v38, v86, s[20:21]
	v_add_u32_e32 v39, 0x58000, v15
	global_store_short v39, v87, s[20:21]
	v_add_u32_e32 v40, 0x80000, v15
	global_store_short v40, v88, s[20:21]
	v_add_u32_e32 v41, 0x88000, v15
	global_store_short v41, v89, s[20:21]
	v_add_u32_e32 v42, 0x90000, v15
	global_store_short v42, v90, s[20:21]
	v_add_u32_e32 v43, 0x98000, v15
	global_store_short v43, v91, s[20:21]
	v_add_u32_e32 v44, 0xc0000, v15
	global_store_short v44, v92, s[20:21]
	v_add_u32_e32 v45, 0xc8000, v15
	global_store_short v45, v93, s[20:21]
	v_add_u32_e32 v46, 0xd0000, v15
	global_store_short v46, v94, s[20:21]
	v_add_u32_e32 v47, 0xd8000, v15
	global_store_short v47, v95, s[20:21]
	s_branch .LBB0_1070
